# MLA attention: waves 4-7 run a rotated (half-tile staggered) copy of the KV loop, bit-identical math
# speedup vs baseline: 1.0048x; 1.0048x over previous
; #define AT_QK_LD0(kb_) do { if constexpr (NEGM) { const LAS unsigned char* kbp_ = Kl + (kb_) * KBUF + r32 * KROWB + hi * 16; AT_KLD2(0); __builtin_amdgcn_sched_barrier(0); } } while (0)
; template <int DQK, int DV, int RH, bool NEGM> ...
;     ...
;     const int NT = nkv / 64;
;     AT_GLOAD(0); AT_LSTORE(0, 0); __syncthreads();
;     int vs_prev = 2, vs_cur = 0, vs_next = 1;
;     if (!grpB) {
;         for (int t = 0; t < NT; ++t) {
;             const int kb = t & 1;
;             if (t + 1 < NT) AT_GLOAD(t + 1);
;             f32x16 p[RH][2];
;             AT_QK_LD0(kb); AT_QK(kb); AT_VLOAD(vs_cur); AT_SOFTMAX(); AT_PV(vs_cur);
;             if (t + 1 < NT) AT_LSTORE(kb ^ 1, vs_next);
;             __syncthreads();
;             vs_prev = vs_cur; vs_cur = vs_next; vs_next = (vs_next == 2) ? 0 : vs_next + 1;
;         }
.LBB0_881:
	s_or_b64 exec, exec, s[42:43]
	v_pk_add_f32 v[48:49], v[48:49], v[54:55]
	v_pk_add_f32 v[64:65], v[128:129], v[64:65]
	v_pk_add_f32 v[48:49], v[58:59], v[48:49] op_sel_hi:[0,1]
	v_pk_add_f32 v[52:53], v[52:53], v[56:57]
	v_pk_add_f32 v[48:49], v[64:65], v[48:49]
	v_pk_add_f32 v[70:71], v[118:119], v[70:71]
	v_pk_add_f32 v[48:49], v[52:53], v[48:49]
	v_add_u32_e32 v54, v136, v135
	v_pk_add_f32 v[150:151], v[70:71], v[48:49]
	v_add_u32_e32 v48, 0x8a00, v166
	s_waitcnt vmcnt(0)
	ds_write2_b64 v48, v[74:75], v[76:77] offset1:1
	v_mul_lo_u32 v48, v54, 12
	v_sub_u32_e32 v52, v133, v48
	s_lshr_b32 s21, s61, 4
	v_lshlrev_b32_e32 v48, 3, v52
	v_lshlrev_b32_e32 v175, 4, v52
	v_mov_b64_e32 v[52:53], s[40:41]
	s_and_b32 s42, s21, 7
	v_mul_lo_u32 v174, v54, s56
	v_mad_i64_i32 v[54:55], s[40:41], v54, s51, v[52:53]
	v_pk_add_f32 v[50:51], v[50:51], v[62:63]
	v_ashrrev_i32_e32 v49, 31, v48
	v_mad_u64_u32 v[54:55], s[40:41], s42, v163, v[54:55]
	v_pk_add_f32 v[66:67], v[130:131], v[66:67]
	v_pk_add_f32 v[50:51], v[58:59], v[50:51] op_sel_hi:[0,1]
	v_lshl_add_u64 v[48:49], v[48:49], 1, v[54:55]
	v_pk_add_f32 v[56:57], v[116:117], v[68:69]
	v_pk_add_f32 v[50:51], v[66:67], v[50:51]
	v_lshl_add_u64 v[154:155], s[28:29], 0, v[48:49]
	v_mad_i64_i32 v[48:49], s[40:41], v59, s51, v[52:53]
	v_pk_add_f32 v[60:61], v[60:61], v[72:73]
	v_pk_add_f32 v[50:51], v[56:57], v[50:51]
	s_lshl_b32 s43, s42, 6
	v_mad_u64_u32 v[48:49], s[40:41], s42, v163, v[48:49]
	v_pk_add_f32 v[152:153], v[60:61], v[50:51]
	v_lshlrev_b32_e32 v50, 3, v112
	s_add_i32 s40, s47, s43
	v_ashrrev_i32_e32 v51, 31, v50
	s_ashr_i32 s41, s40, 31
	v_lshl_add_u64 v[48:49], v[50:51], 1, v[48:49]
	s_lshl_b64 s[40:41], s[40:41], 13
	v_and_b32_e32 v50, 7, v132
	v_lshl_add_u64 v[156:157], s[28:29], 0, v[48:49]
	v_lshl_add_u64 v[48:49], v[78:79], 0, s[40:41]
	v_lshlrev_b32_e32 v148, 4, v50
	v_lshl_add_u64 v[48:49], v[48:49], 0, v[148:149]
	v_mul_u32_u24_e32 v173, 0x88, v134
	s_mov_b32 s21, 1
	v_lshl_add_u64 v[158:159], s[30:31], 0, v[48:49]
	s_mov_b32 s42, 2
	s_mov_b32 s43, 1
	s_waitcnt lgkmcnt(0)
	s_barrier
	s_cmpk_gt_u32 s33, 0xff
	s_cbranch_scc1 .LmlaB_entry
	s_and_saveexec_b64 s[40:41], s[6:7]
	s_cbranch_execz .LBB0_884
	s_branch .LBB0_883

.LmlaA_last:
	ds_read_b128 v[64:67], v169 offset:13312
	ds_read_b128 v[68:71], v169 offset:13344
	ds_read_b128 v[72:75], v169 offset:19968
	ds_read_b128 v[76:79], v169 offset:20000
	s_waitcnt lgkmcnt(3)
	v_mfma_f32_32x32x16_bf16 v[48:63], v[64:67], v[100:103], v[32:47]
	ds_read_b128 v[64:67], v169 offset:13376
	ds_read_b128 v[104:107], v169 offset:13408
	ds_read_b128 v[108:111], v169 offset:20032
	ds_read_b128 v[112:115], v169 offset:20064
	s_waitcnt lgkmcnt(6)
	v_mfma_f32_32x32x16_bf16 v[48:63], v[68:71], v[96:99], v[48:63]
	s_waitcnt lgkmcnt(5)
	v_mfma_f32_32x32x16_bf16 v[32:47], v[72:75], v[100:103], v[32:47]
	s_waitcnt lgkmcnt(4)
	v_mfma_f32_32x32x16_bf16 v[32:47], v[76:79], v[96:99], v[32:47]
	s_waitcnt lgkmcnt(3)
	v_mfma_f32_32x32x16_bf16 v[48:63], v[64:67], v[92:95], v[48:63]
	ds_read_b128 v[64:67], v169 offset:13440
	ds_read_b128 v[68:71], v169 offset:13472
	ds_read_b128 v[72:75], v169 offset:20096
	ds_read_b128 v[76:79], v169 offset:20128
	s_waitcnt lgkmcnt(5)
	v_mfma_f32_32x32x16_bf16 v[32:47], v[108:111], v[92:95], v[32:47]
	v_mfma_f32_32x32x16_bf16 v[48:63], v[104:107], v[88:91], v[48:63]
	s_waitcnt lgkmcnt(4)
	v_mfma_f32_32x32x16_bf16 v[32:47], v[112:115], v[88:91], v[32:47]
	s_waitcnt lgkmcnt(3)
	v_mfma_f32_32x32x16_bf16 v[48:63], v[64:67], v[84:87], v[48:63]
	v_add3_u32 v64, v167, s21, v173
	v_add_u32_e32 v65, 0x6800, v64
	v_add_u32_e32 v64, 0x7800, v64
	ds_read2_b64 v[108:111], v65 offset1:2
	ds_read2_b64 v[104:107], v65 offset0:4 offset1:6
	ds_read2_b64 v[96:99], v65 offset0:8 offset1:10
	ds_read2_b64 v[88:91], v65 offset0:12 offset1:14
	s_waitcnt lgkmcnt(5)
	v_mfma_f32_32x32x16_bf16 v[32:47], v[72:75], v[84:87], v[32:47]
	ds_read2_b64 v[112:115], v64 offset0:32 offset1:34
	ds_read2_b64 v[100:103], v64 offset0:36 offset1:38
	ds_read2_b64 v[92:95], v64 offset0:40 offset1:42
	ds_read2_b64 v[84:87], v64 offset0:44 offset1:46
	v_mfma_f32_32x32x16_bf16 v[48:63], v[68:71], v[80:83], v[48:63]
	s_waitcnt lgkmcnt(8)
	v_mfma_f32_32x32x16_bf16 v[32:47], v[76:79], v[80:83], v[32:47]
	s_nop 11
	v_max_f32_e32 v64, v32, v32
	v_max_f32_e32 v65, v48, v48
	v_max_f32_e32 v64, v65, v64
	v_max_f32_e32 v65, v33, v33
	v_max_f32_e32 v66, v49, v49
	v_max_f32_e32 v65, v66, v65
	v_max_f32_e32 v66, v35, v35
	v_max_f32_e32 v67, v51, v51
	v_max_f32_e32 v66, v67, v66
	v_max3_f32 v67, v50, v34, v54
	v_max3_f32 v66, v66, v55, v39
	v_max3_f32 v64, v64, v52, v36
	v_max3_f32 v65, v65, v53, v37
	v_max3_f32 v67, v67, v38, v58
	v_max3_f32 v66, v66, v59, v43
	v_max3_f32 v64, v64, v56, v40
	v_max3_f32 v65, v65, v57, v41
	v_max3_f32 v67, v67, v42, v62
	v_max3_f32 v66, v66, v63, v47
	v_max3_f32 v64, v64, v60, v44
	v_max3_f32 v65, v65, v61, v45
	v_max3_f32 v66, v67, v46, v66
	v_max3_f32 v64, v64, v65, v66
	v_mov_b32_e32 v65, v64
	s_nop 1
	v_permlane32_swap_b32_e32 v64, v65
	v_max_f32_e32 v65, v65, v65
	v_max_f32_e32 v64, v64, v64
	v_max_f32_e32 v64, v64, v65
	v_cmp_lt_f32_e32 vcc, s59, v64
	s_cbranch_vccnz .LBB0_861
	v_mov_b32_e32 v64, v151
	v_mov_b32_e32 v151, v152
	v_mov_b32_e32 v65, v153
	s_branch .LBB0_862
.LmlaB_entry:
	s_and_saveexec_b64 s[40:41], s[6:7]
	s_cbranch_execz .LmlaB_t884_s
	global_load_dwordx4 v[104:107], v[154:155], off

.LmlaB_t886_s:
	s_or_b64 exec, exec, s[40:41]
	global_load_dwordx4 v[112:115], v[158:159], off
	s_and_b32 s40, s43, 1
	s_mul_i32 s41, s40, 0x3400
	v_add_u32_e32 v140, s41, v169
	ds_read_b128 v[48:51], v140
	ds_read_b128 v[52:55], v140 offset:32
	ds_read_b128 v[116:119], v140 offset:6656
	ds_read_b128 v[120:123], v140 offset:6688
	s_waitcnt lgkmcnt(3)
	v_mfma_f32_32x32x16_bf16 v[64:79], v[48:51], v[100:103], v[32:47]
	ds_read_b128 v[124:127], v140 offset:64
	ds_read_b128 v[128:131], v140 offset:96
	ds_read_b128 v[132:135], v140 offset:6720
	ds_read_b128 v[136:139], v140 offset:6752
	s_waitcnt lgkmcnt(6)
	v_mfma_f32_32x32x16_bf16 v[64:79], v[52:55], v[96:99], v[64:79]
	s_waitcnt lgkmcnt(5)
	v_mfma_f32_32x32x16_bf16 v[48:63], v[116:119], v[100:103], v[32:47]
	s_waitcnt lgkmcnt(4)
	v_mfma_f32_32x32x16_bf16 v[48:63], v[120:123], v[96:99], v[48:63]
	s_waitcnt lgkmcnt(3)
	v_mfma_f32_32x32x16_bf16 v[64:79], v[124:127], v[92:95], v[64:79]
	s_waitcnt lgkmcnt(1)
	v_mfma_f32_32x32x16_bf16 v[48:63], v[132:135], v[92:95], v[48:63]
	v_mfma_f32_32x32x16_bf16 v[64:79], v[128:131], v[88:91], v[64:79]
	ds_read_b128 v[116:119], v140 offset:128
	ds_read_b128 v[120:123], v140 offset:160
	ds_read_b128 v[128:131], v140 offset:6784
	ds_read_b128 v[176:179], v140 offset:6816
	s_waitcnt lgkmcnt(4)
	v_mfma_f32_32x32x16_bf16 v[48:63], v[136:139], v[88:91], v[48:63]
	s_waitcnt lgkmcnt(3)
	v_mfma_f32_32x32x16_bf16 v[64:79], v[116:119], v[84:87], v[64:79]
	s_mulk_i32 s21, 0x2200
	v_add_u32_e32 v116, s21, v170
	v_add_u32_e32 v117, 0x6800, v116
	v_add_u32_e32 v116, 0x7800, v116
	ds_read2_b64 v[136:139], v117 offset1:2
	ds_read2_b64 v[124:127], v117 offset0:4 offset1:6
	s_waitcnt lgkmcnt(3)
	v_mfma_f32_32x32x16_bf16 v[48:63], v[128:131], v[84:87], v[48:63]
	v_mfma_f32_32x32x16_bf16 v[64:79], v[120:123], v[80:83], v[64:79]
	ds_read2_b64 v[132:135], v117 offset0:8 offset1:10
	ds_read2_b64 v[120:123], v117 offset0:12 offset1:14
	ds_read2_b64 v[144:147], v116 offset0:32 offset1:34
	ds_read2_b64 v[140:143], v116 offset0:36 offset1:38
	ds_read2_b64 v[128:131], v116 offset0:40 offset1:42
	ds_read2_b64 v[116:119], v116 offset0:44 offset1:46
	s_waitcnt lgkmcnt(8)
	v_mfma_f32_32x32x16_bf16 v[48:63], v[176:179], v[80:83], v[48:63]
	s_xor_b32 s21, s40, 1
	s_mulk_i32 s21, 0x3400
	s_add_i32 s21, s21, 0
	s_and_saveexec_b64 s[40:41], s[6:7]
	s_cbranch_execz .LmlaB_x890_s
	v_add3_u32 v241, s21, v174, v175
	s_waitcnt vmcnt(1)
	ds_write_b128 v241, v[104:107]
.LmlaB_x890_s:
	s_or_b64 exec, exec, s[40:41]
	s_and_saveexec_b64 s[40:41], s[8:9]
	s_cbranch_execz .LmlaB_x892_s
	v_add3_u32 v241, s21, v171, v172
	s_waitcnt vmcnt(1)
	ds_write_b128 v241, v[108:111]
.LmlaB_x892_s:
	s_or_b64 exec, exec, s[40:41]
	s_add_i32 s43, s43, 1
	s_mul_i32 s21, s42, 0x2200
	s_add_i32 s40, s42, 1
	v_add_u32_e32 v242, s21, v166
	s_cmp_lg_u32 s42, 2
	v_add_u32_e32 v242, 0x6800, v242
	s_cselect_b32 s40, s40, 0
	v_lshl_add_u64 v[154:155], v[154:155], 0, s[34:35]
	v_lshl_add_u64 v[156:157], v[156:157], 0, s[34:35]
	s_cmp_lg_u32 s43, 63
	v_lshl_add_u64 v[158:159], v[158:159], 0, s[36:37]
	s_waitcnt vmcnt(0)
	ds_write2_b64 v242, v[112:113], v[114:115] offset1:1
	s_waitcnt lgkmcnt(0)
	s_barrier
.LmlaB_loop:
	s_mov_b32 s21, s42
	s_mov_b32 s42, s40
	s_and_saveexec_b64 s[40:41], s[6:7]
	s_cbranch_execz .LmlaB_t884_l
	global_load_dwordx4 v[104:107], v[154:155], off

.LmlaB_t886_l:
	s_or_b64 exec, exec, s[40:41]
	global_load_dwordx4 v[112:115], v[158:159], off
	s_nop 11
	v_max_f32_e32 v148, v48, v48
	v_max_f32_e32 v160, v64, v64
	v_max_f32_e32 v148, v160, v148
	v_max_f32_e32 v160, v49, v49
	v_max_f32_e32 v161, v65, v65
	v_max_f32_e32 v160, v161, v160
	v_max_f32_e32 v161, v51, v51
	v_max_f32_e32 v176, v67, v67
	v_max_f32_e32 v161, v176, v161
	v_max3_f32 v176, v66, v50, v70
	v_max3_f32 v161, v161, v71, v55
	v_max3_f32 v148, v148, v68, v52
	v_max3_f32 v160, v160, v69, v53
	v_max3_f32 v176, v176, v54, v74
	v_max3_f32 v161, v161, v75, v59
	v_max3_f32 v148, v148, v72, v56
	v_max3_f32 v160, v160, v73, v57
	v_max3_f32 v176, v176, v58, v78
	v_max3_f32 v161, v161, v79, v63
	v_max3_f32 v148, v148, v76, v60
	v_max3_f32 v160, v160, v77, v61
	v_max3_f32 v161, v176, v62, v161
	v_max3_f32 v148, v148, v160, v161
	v_mov_b32_e32 v160, v148
	s_nop 1
	v_permlane32_swap_b32_e32 v148, v160
	v_max_f32_e32 v160, v160, v160
	v_max_f32_e32 v148, v148, v148
	v_max_f32_e32 v148, v148, v160
	v_cmp_lt_f32_e32 vcc, s59, v148
	s_cbranch_vccz .LmlaB_x888_l
	v_max_f32_e32 v32, v148, v148
	v_max_f32_e32 v148, 0, v32
	v_exp_f32_e64 v160, -v148
	v_add_f32_e32 v168, v168, v148
	v_xor_b32_e32 v32, 0x80000000, v168
	v_mov_b32_e32 v33, v32
	v_mov_b32_e32 v34, v32
	v_mov_b32_e32 v35, v32
	v_mov_b32_e32 v36, v32
	v_mov_b32_e32 v37, v32
	v_mov_b32_e32 v38, v32
	v_mov_b32_e32 v39, v32
	v_mov_b32_e32 v40, v32
	v_mov_b32_e32 v41, v32
	v_mov_b32_e32 v42, v32
	v_mov_b32_e32 v43, v32
	v_mov_b32_e32 v44, v32
	v_mov_b32_e32 v45, v32
	v_mov_b32_e32 v46, v32
	v_mov_b32_e32 v47, v32
	v_pk_add_f32 v[64:65], v[64:65], v[148:149] op_sel_hi:[1,0] neg_lo:[0,1] neg_hi:[0,1]
	v_pk_add_f32 v[48:49], v[48:49], v[148:149] op_sel_hi:[1,0] neg_lo:[0,1] neg_hi:[0,1]
	v_pk_add_f32 v[66:67], v[66:67], v[148:149] op_sel_hi:[1,0] neg_lo:[0,1] neg_hi:[0,1]
	v_pk_add_f32 v[50:51], v[50:51], v[148:149] op_sel_hi:[1,0] neg_lo:[0,1] neg_hi:[0,1]
	v_pk_add_f32 v[68:69], v[68:69], v[148:149] op_sel_hi:[1,0] neg_lo:[0,1] neg_hi:[0,1]
	v_pk_add_f32 v[52:53], v[52:53], v[148:149] op_sel_hi:[1,0] neg_lo:[0,1] neg_hi:[0,1]
	v_pk_add_f32 v[70:71], v[70:71], v[148:149] op_sel_hi:[1,0] neg_lo:[0,1] neg_hi:[0,1]
	v_pk_add_f32 v[54:55], v[54:55], v[148:149] op_sel_hi:[1,0] neg_lo:[0,1] neg_hi:[0,1]
	v_pk_add_f32 v[72:73], v[72:73], v[148:149] op_sel_hi:[1,0] neg_lo:[0,1] neg_hi:[0,1]
	v_pk_add_f32 v[56:57], v[56:57], v[148:149] op_sel_hi:[1,0] neg_lo:[0,1] neg_hi:[0,1]
	v_pk_add_f32 v[74:75], v[74:75], v[148:149] op_sel_hi:[1,0] neg_lo:[0,1] neg_hi:[0,1]
	v_pk_add_f32 v[58:59], v[58:59], v[148:149] op_sel_hi:[1,0] neg_lo:[0,1] neg_hi:[0,1]
	v_pk_add_f32 v[76:77], v[76:77], v[148:149] op_sel_hi:[1,0] neg_lo:[0,1] neg_hi:[0,1]
	v_pk_add_f32 v[60:61], v[60:61], v[148:149] op_sel_hi:[1,0] neg_lo:[0,1] neg_hi:[0,1]
	v_pk_add_f32 v[78:79], v[78:79], v[148:149] op_sel_hi:[1,0] neg_lo:[0,1] neg_hi:[0,1]
	v_pk_add_f32 v[62:63], v[62:63], v[148:149] op_sel_hi:[1,0] neg_lo:[0,1] neg_hi:[0,1]
	v_pk_mul_f32 v[30:31], v[30:31], v[160:161] op_sel_hi:[1,0]
	v_pk_mul_f32 v[28:29], v[28:29], v[160:161] op_sel_hi:[1,0]
	v_pk_mul_f32 v[26:27], v[26:27], v[160:161] op_sel_hi:[1,0]
	v_pk_mul_f32 v[24:25], v[24:25], v[160:161] op_sel_hi:[1,0]
	v_pk_mul_f32 v[22:23], v[22:23], v[160:161] op_sel_hi:[1,0]
	v_pk_mul_f32 v[20:21], v[20:21], v[160:161] op_sel_hi:[1,0]
	v_pk_mul_f32 v[18:19], v[18:19], v[160:161] op_sel_hi:[1,0]
	v_pk_mul_f32 v[16:17], v[16:17], v[160:161] op_sel_hi:[1,0]
	v_pk_mul_f32 v[14:15], v[14:15], v[160:161] op_sel_hi:[1,0]
	v_pk_mul_f32 v[12:13], v[12:13], v[160:161] op_sel_hi:[1,0]
	v_pk_mul_f32 v[10:11], v[10:11], v[160:161] op_sel_hi:[1,0]
	v_pk_mul_f32 v[8:9], v[8:9], v[160:161] op_sel_hi:[1,0]
	v_pk_mul_f32 v[6:7], v[6:7], v[160:161] op_sel_hi:[1,0]
	v_pk_mul_f32 v[4:5], v[4:5], v[160:161] op_sel_hi:[1,0]
	v_pk_mul_f32 v[2:3], v[2:3], v[160:161] op_sel_hi:[1,0]
	v_pk_mul_f32 v[0:1], v[0:1], v[160:161] op_sel_hi:[1,0]
	v_pk_mul_f32 v[152:153], v[152:153], v[160:161] op_sel_hi:[1,0]
	v_pk_mul_f32 v[150:151], v[150:151], v[160:161] op_sel_hi:[1,0]
.LmlaB_x888_l:
	v_exp_f32_e32 v160, v64
	v_exp_f32_e32 v161, v65
	v_exp_f32_e32 v64, v66
	v_exp_f32_e32 v65, v67
	v_exp_f32_e32 v68, v68
	v_exp_f32_e32 v69, v69
	v_exp_f32_e32 v66, v70
	v_exp_f32_e32 v67, v71
	v_cvt_pk_bf16_f32 v176, v160, v161
	v_cvt_pk_bf16_f32 v177, v64, v65
	v_cvt_pk_bf16_f32 v178, v68, v69
	v_cvt_pk_bf16_f32 v179, v66, v67
	v_exp_f32_e32 v70, v74
	v_exp_f32_e32 v71, v75
	s_waitcnt lgkmcnt(7)
	v_mfma_f32_32x32x16_bf16 v[16:31], v[136:139], v[176:179], v[16:31]
	v_exp_f32_e32 v136, v72
	v_exp_f32_e32 v137, v73
	v_exp_f32_e32 v74, v76
	v_exp_f32_e32 v75, v77
	v_exp_f32_e32 v72, v78
	v_exp_f32_e32 v73, v79
	v_exp_f32_e32 v76, v48
	s_waitcnt lgkmcnt(3)
	v_mfma_f32_32x32x16_bf16 v[0:15], v[144:147], v[176:179], v[0:15]
	v_cvt_pk_bf16_f32 v144, v136, v137
	v_cvt_pk_bf16_f32 v145, v70, v71
	v_cvt_pk_bf16_f32 v146, v74, v75
	v_cvt_pk_bf16_f32 v147, v72, v73
	v_exp_f32_e32 v77, v49
	v_exp_f32_e32 v48, v50
	v_exp_f32_e32 v49, v51
	v_mfma_f32_32x32x16_bf16 v[16:31], v[124:127], v[144:147], v[16:31]
	v_exp_f32_e32 v52, v52
	v_exp_f32_e32 v53, v53
	v_exp_f32_e32 v50, v54
	v_exp_f32_e32 v51, v55
	v_cvt_pk_bf16_f32 v124, v76, v77
	v_cvt_pk_bf16_f32 v125, v48, v49
	v_cvt_pk_bf16_f32 v126, v52, v53
	s_waitcnt lgkmcnt(2)
	v_mfma_f32_32x32x16_bf16 v[0:15], v[140:143], v[144:147], v[0:15]
	v_cvt_pk_bf16_f32 v127, v50, v51
	v_exp_f32_e32 v78, v56
	v_exp_f32_e32 v79, v57
	v_exp_f32_e32 v54, v58
	v_exp_f32_e32 v55, v59
	v_exp_f32_e32 v58, v60
	v_exp_f32_e32 v59, v61
	v_mfma_f32_32x32x16_bf16 v[16:31], v[132:135], v[124:127], v[16:31]
	v_exp_f32_e32 v56, v62
	v_exp_f32_e32 v57, v63
	v_cvt_pk_bf16_f32 v60, v78, v79
	v_cvt_pk_bf16_f32 v61, v54, v55
	v_cvt_pk_bf16_f32 v62, v58, v59
	v_cvt_pk_bf16_f32 v63, v56, v57
	s_waitcnt lgkmcnt(1)
	v_mfma_f32_32x32x16_bf16 v[0:15], v[128:131], v[124:127], v[0:15]
	v_mfma_f32_32x32x16_bf16 v[16:31], v[120:123], v[60:63], v[16:31]
	s_waitcnt lgkmcnt(0)
	v_mfma_f32_32x32x16_bf16 v[0:15], v[116:119], v[60:63], v[0:15]
	v_pk_add_f32 v[48:49], v[64:65], v[48:49]
	v_pk_add_f32 v[60:61], v[160:161], v[76:77]
	v_pk_add_f32 v[48:49], v[152:153], v[48:49]
	v_pk_add_f32 v[50:51], v[66:67], v[50:51]
	v_pk_add_f32 v[60:61], v[150:151], v[60:61]
	v_pk_add_f32 v[52:53], v[68:69], v[52:53]
	v_pk_add_f32 v[48:49], v[50:51], v[48:49]
	v_pk_add_f32 v[50:51], v[70:71], v[54:55]
	v_pk_add_f32 v[52:53], v[52:53], v[60:61]
	v_pk_add_f32 v[60:61], v[136:137], v[78:79]
	v_pk_add_f32 v[48:49], v[50:51], v[48:49]
	v_pk_add_f32 v[50:51], v[72:73], v[56:57]
	v_pk_add_f32 v[52:53], v[60:61], v[52:53]
	v_pk_add_f32 v[58:59], v[74:75], v[58:59]
	v_pk_add_f32 v[152:153], v[50:51], v[48:49]
	v_pk_add_f32 v[150:151], v[58:59], v[52:53]
	s_and_b32 s40, s43, 1
	s_mul_i32 s41, s40, 0x3400
	v_add_u32_e32 v140, s41, v169
	ds_read_b128 v[48:51], v140
	ds_read_b128 v[52:55], v140 offset:32
	ds_read_b128 v[116:119], v140 offset:6656
	ds_read_b128 v[120:123], v140 offset:6688
	s_waitcnt lgkmcnt(3)
	v_mfma_f32_32x32x16_bf16 v[64:79], v[48:51], v[100:103], v[32:47]
	ds_read_b128 v[124:127], v140 offset:64
	ds_read_b128 v[128:131], v140 offset:96
	ds_read_b128 v[132:135], v140 offset:6720
	ds_read_b128 v[136:139], v140 offset:6752
	s_waitcnt lgkmcnt(6)
	v_mfma_f32_32x32x16_bf16 v[64:79], v[52:55], v[96:99], v[64:79]
	s_waitcnt lgkmcnt(5)
	v_mfma_f32_32x32x16_bf16 v[48:63], v[116:119], v[100:103], v[32:47]
	s_waitcnt lgkmcnt(4)
	v_mfma_f32_32x32x16_bf16 v[48:63], v[120:123], v[96:99], v[48:63]
	s_waitcnt lgkmcnt(3)
	v_mfma_f32_32x32x16_bf16 v[64:79], v[124:127], v[92:95], v[64:79]
	s_waitcnt lgkmcnt(1)
	v_mfma_f32_32x32x16_bf16 v[48:63], v[132:135], v[92:95], v[48:63]
	v_mfma_f32_32x32x16_bf16 v[64:79], v[128:131], v[88:91], v[64:79]
	ds_read_b128 v[116:119], v140 offset:128
	ds_read_b128 v[120:123], v140 offset:160
	ds_read_b128 v[128:131], v140 offset:6784
	ds_read_b128 v[176:179], v140 offset:6816
	s_waitcnt lgkmcnt(4)
	v_mfma_f32_32x32x16_bf16 v[48:63], v[136:139], v[88:91], v[48:63]
	s_waitcnt lgkmcnt(3)
	v_mfma_f32_32x32x16_bf16 v[64:79], v[116:119], v[84:87], v[64:79]
	s_mulk_i32 s21, 0x2200
	v_add_u32_e32 v116, s21, v170
	v_add_u32_e32 v117, 0x6800, v116
	v_add_u32_e32 v116, 0x7800, v116
	ds_read2_b64 v[136:139], v117 offset1:2
	ds_read2_b64 v[124:127], v117 offset0:4 offset1:6
	s_waitcnt lgkmcnt(3)
	v_mfma_f32_32x32x16_bf16 v[48:63], v[128:131], v[84:87], v[48:63]
	v_mfma_f32_32x32x16_bf16 v[64:79], v[120:123], v[80:83], v[64:79]
	ds_read2_b64 v[132:135], v117 offset0:8 offset1:10
	ds_read2_b64 v[120:123], v117 offset0:12 offset1:14
	ds_read2_b64 v[144:147], v116 offset0:32 offset1:34
	ds_read2_b64 v[140:143], v116 offset0:36 offset1:38
	ds_read2_b64 v[128:131], v116 offset0:40 offset1:42
	ds_read2_b64 v[116:119], v116 offset0:44 offset1:46
	s_waitcnt lgkmcnt(8)
	v_mfma_f32_32x32x16_bf16 v[48:63], v[176:179], v[80:83], v[48:63]
	s_xor_b32 s21, s40, 1
	s_mulk_i32 s21, 0x3400
	s_add_i32 s21, s21, 0
	s_and_saveexec_b64 s[40:41], s[6:7]
	s_cbranch_execz .LmlaB_x890_l
	v_add3_u32 v241, s21, v174, v175
	s_waitcnt vmcnt(1)
	ds_write_b128 v241, v[104:107]

.LmlaB_x892_l:
	s_or_b64 exec, exec, s[40:41]
	s_add_i32 s43, s43, 1
	s_mul_i32 s21, s42, 0x2200
	s_add_i32 s40, s42, 1
	v_add_u32_e32 v242, s21, v166
	s_cmp_lg_u32 s42, 2
	v_add_u32_e32 v242, 0x6800, v242
	s_cselect_b32 s40, s40, 0
	v_lshl_add_u64 v[154:155], v[154:155], 0, s[34:35]
	v_lshl_add_u64 v[156:157], v[156:157], 0, s[34:35]
	s_cmp_lg_u32 s43, 63
	v_lshl_add_u64 v[158:159], v[158:159], 0, s[36:37]
	s_waitcnt vmcnt(0)
	ds_write2_b64 v242, v[112:113], v[114:115] offset1:1
	s_waitcnt lgkmcnt(0)
	s_barrier
	s_cbranch_scc1 .LmlaB_loop
	s_nop 11
	v_max_f32_e32 v148, v48, v48
	v_max_f32_e32 v160, v64, v64
	v_max_f32_e32 v148, v160, v148
	v_max_f32_e32 v160, v49, v49
	v_max_f32_e32 v161, v65, v65
	v_max_f32_e32 v160, v161, v160
	v_max_f32_e32 v161, v51, v51
	v_max_f32_e32 v176, v67, v67
	v_max_f32_e32 v161, v176, v161
	v_max3_f32 v176, v66, v50, v70
	v_max3_f32 v161, v161, v71, v55
	v_max3_f32 v148, v148, v68, v52
	v_max3_f32 v160, v160, v69, v53
	v_max3_f32 v176, v176, v54, v74
	v_max3_f32 v161, v161, v75, v59
	v_max3_f32 v148, v148, v72, v56
	v_max3_f32 v160, v160, v73, v57
	v_max3_f32 v176, v176, v58, v78
	v_max3_f32 v161, v161, v79, v63
	v_max3_f32 v148, v148, v76, v60
	v_max3_f32 v160, v160, v77, v61
	v_max3_f32 v161, v176, v62, v161
	v_max3_f32 v148, v148, v160, v161
	v_mov_b32_e32 v160, v148
	s_nop 1
	v_permlane32_swap_b32_e32 v148, v160
	v_max_f32_e32 v160, v160, v160
	v_max_f32_e32 v148, v148, v148
	v_max_f32_e32 v148, v148, v160
	v_cmp_lt_f32_e32 vcc, s59, v148
	s_cbranch_vccz .LmlaB_x888_t
	v_max_f32_e32 v32, v148, v148
	v_max_f32_e32 v148, 0, v32
	v_exp_f32_e64 v160, -v148
	v_add_f32_e32 v168, v168, v148
	v_xor_b32_e32 v32, 0x80000000, v168
	v_mov_b32_e32 v33, v32
	v_mov_b32_e32 v34, v32
	v_mov_b32_e32 v35, v32
	v_mov_b32_e32 v36, v32
	v_mov_b32_e32 v37, v32
	v_mov_b32_e32 v38, v32
	v_mov_b32_e32 v39, v32
	v_mov_b32_e32 v40, v32
	v_mov_b32_e32 v41, v32
	v_mov_b32_e32 v42, v32
	v_mov_b32_e32 v43, v32
	v_mov_b32_e32 v44, v32
	v_mov_b32_e32 v45, v32
	v_mov_b32_e32 v46, v32
	v_mov_b32_e32 v47, v32
	v_pk_add_f32 v[64:65], v[64:65], v[148:149] op_sel_hi:[1,0] neg_lo:[0,1] neg_hi:[0,1]
	v_pk_add_f32 v[48:49], v[48:49], v[148:149] op_sel_hi:[1,0] neg_lo:[0,1] neg_hi:[0,1]
	v_pk_add_f32 v[66:67], v[66:67], v[148:149] op_sel_hi:[1,0] neg_lo:[0,1] neg_hi:[0,1]
	v_pk_add_f32 v[50:51], v[50:51], v[148:149] op_sel_hi:[1,0] neg_lo:[0,1] neg_hi:[0,1]
	v_pk_add_f32 v[68:69], v[68:69], v[148:149] op_sel_hi:[1,0] neg_lo:[0,1] neg_hi:[0,1]
	v_pk_add_f32 v[52:53], v[52:53], v[148:149] op_sel_hi:[1,0] neg_lo:[0,1] neg_hi:[0,1]
	v_pk_add_f32 v[70:71], v[70:71], v[148:149] op_sel_hi:[1,0] neg_lo:[0,1] neg_hi:[0,1]
	v_pk_add_f32 v[54:55], v[54:55], v[148:149] op_sel_hi:[1,0] neg_lo:[0,1] neg_hi:[0,1]
	v_pk_add_f32 v[72:73], v[72:73], v[148:149] op_sel_hi:[1,0] neg_lo:[0,1] neg_hi:[0,1]
	v_pk_add_f32 v[56:57], v[56:57], v[148:149] op_sel_hi:[1,0] neg_lo:[0,1] neg_hi:[0,1]
	v_pk_add_f32 v[74:75], v[74:75], v[148:149] op_sel_hi:[1,0] neg_lo:[0,1] neg_hi:[0,1]
	v_pk_add_f32 v[58:59], v[58:59], v[148:149] op_sel_hi:[1,0] neg_lo:[0,1] neg_hi:[0,1]
	v_pk_add_f32 v[76:77], v[76:77], v[148:149] op_sel_hi:[1,0] neg_lo:[0,1] neg_hi:[0,1]
	v_pk_add_f32 v[60:61], v[60:61], v[148:149] op_sel_hi:[1,0] neg_lo:[0,1] neg_hi:[0,1]
	v_pk_add_f32 v[78:79], v[78:79], v[148:149] op_sel_hi:[1,0] neg_lo:[0,1] neg_hi:[0,1]
	v_pk_add_f32 v[62:63], v[62:63], v[148:149] op_sel_hi:[1,0] neg_lo:[0,1] neg_hi:[0,1]
	v_pk_mul_f32 v[30:31], v[30:31], v[160:161] op_sel_hi:[1,0]
	v_pk_mul_f32 v[28:29], v[28:29], v[160:161] op_sel_hi:[1,0]
	v_pk_mul_f32 v[26:27], v[26:27], v[160:161] op_sel_hi:[1,0]
	v_pk_mul_f32 v[24:25], v[24:25], v[160:161] op_sel_hi:[1,0]
	v_pk_mul_f32 v[22:23], v[22:23], v[160:161] op_sel_hi:[1,0]
	v_pk_mul_f32 v[20:21], v[20:21], v[160:161] op_sel_hi:[1,0]
	v_pk_mul_f32 v[18:19], v[18:19], v[160:161] op_sel_hi:[1,0]
	v_pk_mul_f32 v[16:17], v[16:17], v[160:161] op_sel_hi:[1,0]
	v_pk_mul_f32 v[14:15], v[14:15], v[160:161] op_sel_hi:[1,0]
	v_pk_mul_f32 v[12:13], v[12:13], v[160:161] op_sel_hi:[1,0]
	v_pk_mul_f32 v[10:11], v[10:11], v[160:161] op_sel_hi:[1,0]
	v_pk_mul_f32 v[8:9], v[8:9], v[160:161] op_sel_hi:[1,0]
	v_pk_mul_f32 v[6:7], v[6:7], v[160:161] op_sel_hi:[1,0]
	v_pk_mul_f32 v[4:5], v[4:5], v[160:161] op_sel_hi:[1,0]
	v_pk_mul_f32 v[2:3], v[2:3], v[160:161] op_sel_hi:[1,0]
	v_pk_mul_f32 v[0:1], v[0:1], v[160:161] op_sel_hi:[1,0]
	v_pk_mul_f32 v[152:153], v[152:153], v[160:161] op_sel_hi:[1,0]
	v_pk_mul_f32 v[150:151], v[150:151], v[160:161] op_sel_hi:[1,0]
.LmlaB_x888_t:
	v_exp_f32_e32 v160, v64
	v_exp_f32_e32 v161, v65
	v_exp_f32_e32 v64, v66
	v_exp_f32_e32 v65, v67
	v_exp_f32_e32 v68, v68
	v_exp_f32_e32 v69, v69
	v_exp_f32_e32 v66, v70
	v_exp_f32_e32 v67, v71
	v_cvt_pk_bf16_f32 v176, v160, v161
	v_cvt_pk_bf16_f32 v177, v64, v65
	v_cvt_pk_bf16_f32 v178, v68, v69
	v_cvt_pk_bf16_f32 v179, v66, v67
	v_exp_f32_e32 v70, v74
	v_exp_f32_e32 v71, v75
	s_waitcnt lgkmcnt(7)
	v_mfma_f32_32x32x16_bf16 v[16:31], v[136:139], v[176:179], v[16:31]
	v_exp_f32_e32 v136, v72
	v_exp_f32_e32 v137, v73
	v_exp_f32_e32 v74, v76
	v_exp_f32_e32 v75, v77
	v_exp_f32_e32 v72, v78
	v_exp_f32_e32 v73, v79
	v_exp_f32_e32 v76, v48
	s_waitcnt lgkmcnt(3)
	v_mfma_f32_32x32x16_bf16 v[0:15], v[144:147], v[176:179], v[0:15]
	v_cvt_pk_bf16_f32 v144, v136, v137
	v_cvt_pk_bf16_f32 v145, v70, v71
	v_cvt_pk_bf16_f32 v146, v74, v75
	v_cvt_pk_bf16_f32 v147, v72, v73
	v_exp_f32_e32 v77, v49
	v_exp_f32_e32 v48, v50
	v_exp_f32_e32 v49, v51
	v_mfma_f32_32x32x16_bf16 v[16:31], v[124:127], v[144:147], v[16:31]
	v_exp_f32_e32 v52, v52
	v_exp_f32_e32 v53, v53
	v_exp_f32_e32 v50, v54
	v_exp_f32_e32 v51, v55
	v_cvt_pk_bf16_f32 v124, v76, v77
	v_cvt_pk_bf16_f32 v125, v48, v49
	v_cvt_pk_bf16_f32 v126, v52, v53
	s_waitcnt lgkmcnt(2)
	v_mfma_f32_32x32x16_bf16 v[0:15], v[140:143], v[144:147], v[0:15]
	v_cvt_pk_bf16_f32 v127, v50, v51
	v_exp_f32_e32 v78, v56
	v_exp_f32_e32 v79, v57
	v_exp_f32_e32 v54, v58
	v_exp_f32_e32 v55, v59
	v_exp_f32_e32 v58, v60
	v_exp_f32_e32 v59, v61
	v_mfma_f32_32x32x16_bf16 v[16:31], v[132:135], v[124:127], v[16:31]
	v_exp_f32_e32 v56, v62
	v_exp_f32_e32 v57, v63
	v_cvt_pk_bf16_f32 v60, v78, v79
	v_cvt_pk_bf16_f32 v61, v54, v55
	v_cvt_pk_bf16_f32 v62, v58, v59
	v_cvt_pk_bf16_f32 v63, v56, v57
	s_waitcnt lgkmcnt(1)
	v_mfma_f32_32x32x16_bf16 v[0:15], v[128:131], v[124:127], v[0:15]
	v_mfma_f32_32x32x16_bf16 v[16:31], v[120:123], v[60:63], v[16:31]
	s_waitcnt lgkmcnt(0)
	v_mfma_f32_32x32x16_bf16 v[0:15], v[116:119], v[60:63], v[0:15]
	v_pk_add_f32 v[48:49], v[64:65], v[48:49]
	v_pk_add_f32 v[60:61], v[160:161], v[76:77]
	v_pk_add_f32 v[48:49], v[152:153], v[48:49]
	v_pk_add_f32 v[50:51], v[66:67], v[50:51]
	v_pk_add_f32 v[60:61], v[150:151], v[60:61]
	v_pk_add_f32 v[52:53], v[68:69], v[52:53]
	v_pk_add_f32 v[48:49], v[50:51], v[48:49]
	v_pk_add_f32 v[50:51], v[70:71], v[54:55]
	v_pk_add_f32 v[52:53], v[52:53], v[60:61]
	v_pk_add_f32 v[60:61], v[136:137], v[78:79]
	v_pk_add_f32 v[48:49], v[50:51], v[48:49]
	v_pk_add_f32 v[50:51], v[72:73], v[56:57]
	v_pk_add_f32 v[52:53], v[60:61], v[52:53]
	v_pk_add_f32 v[58:59], v[74:75], v[58:59]
	v_pk_add_f32 v[152:153], v[50:51], v[48:49]
	v_pk_add_f32 v[150:151], v[58:59], v[52:53]
	s_branch .LmlaA_last

; __global__ void __launch_bounds__(512, 2) fwd_mega(Args a) {
	.amdhsa_kernel _Z8fwd_mega4Args
		.amdhsa_group_segment_fixed_size 0
		.amdhsa_private_segment_fixed_size 0
		.amdhsa_kernarg_size 496
		.amdhsa_user_sgpr_count 2
		.amdhsa_user_sgpr_dispatch_ptr 0
		.amdhsa_user_sgpr_queue_ptr 0
		.amdhsa_user_sgpr_kernarg_segment_ptr 1
		.amdhsa_user_sgpr_dispatch_id 0
		.amdhsa_user_sgpr_kernarg_preload_length 0
		.amdhsa_user_sgpr_kernarg_preload_offset 0
		.amdhsa_user_sgpr_private_segment_size 0
		.amdhsa_uses_dynamic_stack 0
		.amdhsa_enable_private_segment 0
		.amdhsa_system_sgpr_workgroup_id_x 1
		.amdhsa_system_sgpr_workgroup_id_y 0
		.amdhsa_system_sgpr_workgroup_id_z 0
		.amdhsa_system_sgpr_workgroup_info 0
		.amdhsa_system_vgpr_workitem_id 2
		.amdhsa_next_free_vgpr 243
		.amdhsa_next_free_sgpr 98
		.amdhsa_accum_offset 244
		.amdhsa_reserve_vcc 1
		.amdhsa_float_round_mode_32 0
		.amdhsa_float_round_mode_16_64 0
		.amdhsa_float_denorm_mode_32 3
		.amdhsa_float_denorm_mode_16_64 3
		.amdhsa_dx10_clamp 1
		.amdhsa_ieee_mode 1
		.amdhsa_fp16_overflow 0
		.amdhsa_tg_split 0
		.amdhsa_exception_fp_ieee_invalid_op 0
		.amdhsa_exception_fp_denorm_src 0
		.amdhsa_exception_fp_ieee_div_zero 0
		.amdhsa_exception_fp_ieee_overflow 0
		.amdhsa_exception_fp_ieee_underflow 0
		.amdhsa_exception_fp_ieee_inexact 0
		.amdhsa_exception_int_div_zero 0
	.end_amdhsa_kernel

; __global__ void __launch_bounds__(512, 2) fwd_mega(Args a) {
.Lfunc_end0:
	.size	_Z8fwd_mega4Args, .Lfunc_end0-_Z8fwd_mega4Args
	.set _Z8fwd_mega4Args.num_vgpr, 243
	.set _Z8fwd_mega4Args.num_agpr, 0
	.set _Z8fwd_mega4Args.numbered_sgpr, 98
	.set _Z8fwd_mega4Args.num_named_barrier, 0
	.set _Z8fwd_mega4Args.private_seg_size, 0
	.set _Z8fwd_mega4Args.uses_vcc, 1
	.set _Z8fwd_mega4Args.uses_flat_scratch, 0
	.set _Z8fwd_mega4Args.has_dyn_sized_stack, 0
	.set _Z8fwd_mega4Args.has_recursion, 0
	.set _Z8fwd_mega4Args.has_indirect_call, 0

; __global__ void __launch_bounds__(512, 2) fwd_mega(Args a) {
amdhsa.kernels:
  - .agpr_count:     0
    .args:
      - .offset:         0
        .size:           240
        .value_kind:     by_value
      - .offset:         240
        .size:           4
        .value_kind:     hidden_block_count_x
      - .offset:         244
        .size:           4
        .value_kind:     hidden_block_count_y
      - .offset:         248
        .size:           4
        .value_kind:     hidden_block_count_z
      - .offset:         252
        .size:           2
        .value_kind:     hidden_group_size_x
      - .offset:         254
        .size:           2
        .value_kind:     hidden_group_size_y
      - .offset:         256
        .size:           2
        .value_kind:     hidden_group_size_z
      - .offset:         258
        .size:           2
        .value_kind:     hidden_remainder_x
      - .offset:         260
        .size:           2
        .value_kind:     hidden_remainder_y
      - .offset:         262
        .size:           2
        .value_kind:     hidden_remainder_z
      - .offset:         280
        .size:           8
        .value_kind:     hidden_global_offset_x
      - .offset:         288
        .size:           8
        .value_kind:     hidden_global_offset_y
      - .offset:         296
        .size:           8
        .value_kind:     hidden_global_offset_z
      - .offset:         304
        .size:           2
        .value_kind:     hidden_grid_dims
      - .offset:         328
        .size:           8
        .value_kind:     hidden_multigrid_sync_arg
      - .offset:         360
        .size:           4
        .value_kind:     hidden_dynamic_lds_size
    .group_segment_fixed_size: 0
    .kernarg_segment_align: 8
    .kernarg_segment_size: 496
    .language:       OpenCL C
    .language_version:
      - 2
      - 0
    .max_flat_workgroup_size: 512
    .name:           _Z8fwd_mega4Args
    .private_segment_fixed_size: 0
    .sgpr_count:     104
    .sgpr_spill_count: 6
    .symbol:         _Z8fwd_mega4Args.kd
    .uniform_work_group_size: 1
    .uses_dynamic_stack: false
    .vgpr_count:     243
    .vgpr_spill_count: 0
    .wavefront_size: 64
